# ph0 adaLN GEMV: weight rows prefetched 3 groups ahead (12-16 loads per lane in flight instead of 4), same arithmetic
# speedup vs baseline: 1.0105x; 1.0105x over previous
.LBB0_686:
	s_mul_hi_i32 s0, s9, 0x38e38e39
	s_lshr_b32 s1, s0, 31
	s_ashr_i32 s0, s0, 3
	v_mov_b32_e32 v0, s14
	ds_read_b64 v[0:1], v0
	s_add_i32 s0, s0, s1
	s_mul_i32 s1, s0, 36
	s_sub_i32 s1, s9, s1
	s_lshl_b32 s4, s1, 8
	s_ashr_i32 s5, s4, 31
	s_waitcnt lgkmcnt(0)
	v_readfirstlane_b32 s7, v1
	v_readfirstlane_b32 s6, v0
	s_ashr_i32 s1, s0, 31
	s_mul_i32 s11, s0, 0x2400000
	s_lshl_b64 s[4:5], s[4:5], 2
	s_mul_hi_i32 s10, s0, 0x2400000
	v_lshl_add_u64 v[0:1], s[6:7], 0, v[34:35]
	s_add_u32 s6, s11, s4
	s_addc_u32 s7, s10, s5
	v_lshl_add_u64 v[36:37], v[0:1], 0, s[6:7]
	v_mov_b32_e32 v0, 0
	s_mov_b64 s[6:7], 0
	s_mov_b32 s10, s8
	v_mov_b32_e32 v1, v0
	v_mov_b32_e32 v2, v0
	v_mov_b32_e32 v3, v0
	v_mov_b32_e32 v4, v0
	v_mov_b32_e32 v5, v0
	v_mov_b32_e32 v6, v0
	v_mov_b32_e32 v7, v0
	v_mov_b32_e32 v8, v0
	v_mov_b32_e32 v9, v0
	v_mov_b32_e32 v10, v0
	v_mov_b32_e32 v11, v0
	v_mov_b32_e32 v12, v0
	v_mov_b32_e32 v13, v0
	v_mov_b32_e32 v14, v0
	v_mov_b32_e32 v15, v0
	v_mov_b32_e32 v16, v0
	v_mov_b32_e32 v17, v0
	v_mov_b32_e32 v18, v0
	v_mov_b32_e32 v19, v0
	v_mov_b32_e32 v20, v0
	v_mov_b32_e32 v21, v0
	v_mov_b32_e32 v22, v0
	v_mov_b32_e32 v23, v0
	v_mov_b32_e32 v24, v0
	v_mov_b32_e32 v25, v0
	v_mov_b32_e32 v26, v0
	v_mov_b32_e32 v27, v0
	v_mov_b32_e32 v28, v0
	v_mov_b32_e32 v29, v0
	v_mov_b32_e32 v30, v0
	v_mov_b32_e32 v31, v0
	v_add_co_u32_e32 v178, vcc, s54, v36
	v_addc_co_u32_e32 v179, vcc, 0, v37, vcc
	v_add_co_u32_e32 v180, vcc, s59, v36
	v_addc_co_u32_e32 v181, vcc, 0, v37, vcc
	s_mov_b32 s11, 0x1b000
	v_add_co_u32_e32 v182, vcc, s11, v36
	v_addc_co_u32_e32 v183, vcc, 0, v37, vcc
	v_lshl_add_u64 v[38:39], v[36:37], 0, s[6:7]
	global_load_dwordx4 v[44:47], v[38:39], off nt
	v_lshl_add_u64 v[38:39], v[178:179], 0, s[6:7]
	global_load_dwordx4 v[48:51], v[38:39], off nt
	v_lshl_add_u64 v[38:39], v[180:181], 0, s[6:7]
	global_load_dwordx4 v[52:55], v[38:39], off nt
	v_lshl_add_u64 v[38:39], v[182:183], 0, s[6:7]
	global_load_dwordx4 v[56:59], v[38:39], off nt
	s_add_u32 s6, s6, 0x24000
	v_lshl_add_u64 v[38:39], v[36:37], 0, s[6:7]
	global_load_dwordx4 v[60:63], v[38:39], off nt
	v_lshl_add_u64 v[38:39], v[178:179], 0, s[6:7]
	global_load_dwordx4 v[64:67], v[38:39], off nt
	v_lshl_add_u64 v[38:39], v[180:181], 0, s[6:7]
	global_load_dwordx4 v[68:71], v[38:39], off nt
	v_lshl_add_u64 v[38:39], v[182:183], 0, s[6:7]
	global_load_dwordx4 v[72:75], v[38:39], off nt
	s_add_u32 s6, s6, 0x24000
	v_lshl_add_u64 v[38:39], v[36:37], 0, s[6:7]
	global_load_dwordx4 v[94:97], v[38:39], off nt
	v_lshl_add_u64 v[38:39], v[178:179], 0, s[6:7]
	global_load_dwordx4 v[98:101], v[38:39], off nt
	v_lshl_add_u64 v[38:39], v[180:181], 0, s[6:7]
	global_load_dwordx4 v[102:105], v[38:39], off nt
	v_lshl_add_u64 v[38:39], v[182:183], 0, s[6:7]
	global_load_dwordx4 v[106:109], v[38:39], off nt
	s_add_u32 s6, s6, 0x24000
	s_add_i32 s11, s8, 0x200
.Lada_k:
	v_mov_b32_e32 v43, s10
	ds_read_b128 v[146:149], v43
	ds_read_b128 v[150:153], v43 offset:4096
	ds_read_b128 v[154:157], v43 offset:8192
	ds_read_b128 v[158:161], v43 offset:12288
	ds_read_b128 v[162:165], v43 offset:16384
	ds_read_b128 v[166:169], v43 offset:20480
	ds_read_b128 v[170:173], v43 offset:24576
	ds_read_b128 v[174:177], v43 offset:28672
	s_add_i32 s10, s10, 16
	v_lshl_add_u64 v[38:39], v[36:37], 0, s[6:7]
	global_load_dwordx4 v[110:113], v[38:39], off nt
	v_lshl_add_u64 v[38:39], v[178:179], 0, s[6:7]
	global_load_dwordx4 v[114:117], v[38:39], off nt
	v_lshl_add_u64 v[38:39], v[180:181], 0, s[6:7]
	global_load_dwordx4 v[118:121], v[38:39], off nt
	v_lshl_add_u64 v[38:39], v[182:183], 0, s[6:7]
	global_load_dwordx4 v[122:125], v[38:39], off nt
	s_add_u32 s6, s6, 0x24000
	s_min_u32 s6, s6, 0x45c000
	s_waitcnt vmcnt(12)
	s_waitcnt lgkmcnt(0)
	v_pk_mul_f32 v[128:129], v[50:51], v[146:147] op_sel:[0,1]
	v_pk_mul_f32 v[126:127], v[48:49], v[146:147] op_sel:[0,1]
	v_pk_fma_f32 v[128:129], v[46:47], v[146:147], v[128:129] op_sel_hi:[1,0,1]
	v_pk_fma_f32 v[126:127], v[44:45], v[146:147], v[126:127] op_sel_hi:[1,0,1]
	v_pk_fma_f32 v[128:129], v[54:55], v[148:149], v[128:129] op_sel_hi:[1,0,1]
	v_pk_fma_f32 v[126:127], v[52:53], v[148:149], v[126:127] op_sel_hi:[1,0,1]
	v_pk_fma_f32 v[128:129], v[58:59], v[148:149], v[128:129] op_sel:[0,1,0]
	v_pk_fma_f32 v[126:127], v[56:57], v[148:149], v[126:127] op_sel:[0,1,0]
	v_pk_add_f32 v[30:31], v[30:31], v[128:129]
	v_pk_add_f32 v[28:29], v[28:29], v[126:127]
	v_pk_mul_f32 v[132:133], v[50:51], v[150:151] op_sel:[0,1]
	v_pk_mul_f32 v[130:131], v[48:49], v[150:151] op_sel:[0,1]
	v_pk_fma_f32 v[132:133], v[46:47], v[150:151], v[132:133] op_sel_hi:[1,0,1]
	v_pk_fma_f32 v[130:131], v[44:45], v[150:151], v[130:131] op_sel_hi:[1,0,1]
	v_pk_fma_f32 v[132:133], v[54:55], v[152:153], v[132:133] op_sel_hi:[1,0,1]
	v_pk_fma_f32 v[130:131], v[52:53], v[152:153], v[130:131] op_sel_hi:[1,0,1]
	v_pk_fma_f32 v[132:133], v[58:59], v[152:153], v[132:133] op_sel:[0,1,0]
	v_pk_fma_f32 v[130:131], v[56:57], v[152:153], v[130:131] op_sel:[0,1,0]
	v_pk_add_f32 v[26:27], v[26:27], v[132:133]
	v_pk_add_f32 v[24:25], v[24:25], v[130:131]
	v_pk_mul_f32 v[136:137], v[50:51], v[154:155] op_sel:[0,1]
	v_pk_mul_f32 v[134:135], v[48:49], v[154:155] op_sel:[0,1]
	v_pk_fma_f32 v[136:137], v[46:47], v[154:155], v[136:137] op_sel_hi:[1,0,1]
	v_pk_fma_f32 v[134:135], v[44:45], v[154:155], v[134:135] op_sel_hi:[1,0,1]
	v_pk_fma_f32 v[136:137], v[54:55], v[156:157], v[136:137] op_sel_hi:[1,0,1]
	v_pk_fma_f32 v[134:135], v[52:53], v[156:157], v[134:135] op_sel_hi:[1,0,1]
	v_pk_fma_f32 v[136:137], v[58:59], v[156:157], v[136:137] op_sel:[0,1,0]
	v_pk_fma_f32 v[134:135], v[56:57], v[156:157], v[134:135] op_sel:[0,1,0]
	v_pk_add_f32 v[22:23], v[22:23], v[136:137]
	v_pk_add_f32 v[20:21], v[20:21], v[134:135]
	v_pk_mul_f32 v[140:141], v[50:51], v[158:159] op_sel:[0,1]
	v_pk_mul_f32 v[138:139], v[48:49], v[158:159] op_sel:[0,1]
	v_pk_fma_f32 v[140:141], v[46:47], v[158:159], v[140:141] op_sel_hi:[1,0,1]
	v_pk_fma_f32 v[138:139], v[44:45], v[158:159], v[138:139] op_sel_hi:[1,0,1]
	v_pk_fma_f32 v[140:141], v[54:55], v[160:161], v[140:141] op_sel_hi:[1,0,1]
	v_pk_fma_f32 v[138:139], v[52:53], v[160:161], v[138:139] op_sel_hi:[1,0,1]
	v_pk_fma_f32 v[140:141], v[58:59], v[160:161], v[140:141] op_sel:[0,1,0]
	v_pk_fma_f32 v[138:139], v[56:57], v[160:161], v[138:139] op_sel:[0,1,0]
	v_pk_add_f32 v[18:19], v[18:19], v[140:141]
	v_pk_add_f32 v[16:17], v[16:17], v[138:139]
	v_pk_mul_f32 v[128:129], v[50:51], v[162:163] op_sel:[0,1]
	v_pk_mul_f32 v[126:127], v[48:49], v[162:163] op_sel:[0,1]
	v_pk_fma_f32 v[128:129], v[46:47], v[162:163], v[128:129] op_sel_hi:[1,0,1]
	v_pk_fma_f32 v[126:127], v[44:45], v[162:163], v[126:127] op_sel_hi:[1,0,1]
	v_pk_fma_f32 v[128:129], v[54:55], v[164:165], v[128:129] op_sel_hi:[1,0,1]
	v_pk_fma_f32 v[126:127], v[52:53], v[164:165], v[126:127] op_sel_hi:[1,0,1]
	v_pk_fma_f32 v[128:129], v[58:59], v[164:165], v[128:129] op_sel:[0,1,0]
	v_pk_fma_f32 v[126:127], v[56:57], v[164:165], v[126:127] op_sel:[0,1,0]
	v_pk_add_f32 v[14:15], v[14:15], v[128:129]
	v_pk_add_f32 v[12:13], v[12:13], v[126:127]
	v_pk_mul_f32 v[132:133], v[50:51], v[166:167] op_sel:[0,1]
	v_pk_mul_f32 v[130:131], v[48:49], v[166:167] op_sel:[0,1]
	v_pk_fma_f32 v[132:133], v[46:47], v[166:167], v[132:133] op_sel_hi:[1,0,1]
	v_pk_fma_f32 v[130:131], v[44:45], v[166:167], v[130:131] op_sel_hi:[1,0,1]
	v_pk_fma_f32 v[132:133], v[54:55], v[168:169], v[132:133] op_sel_hi:[1,0,1]
	v_pk_fma_f32 v[130:131], v[52:53], v[168:169], v[130:131] op_sel_hi:[1,0,1]
	v_pk_fma_f32 v[132:133], v[58:59], v[168:169], v[132:133] op_sel:[0,1,0]
	v_pk_fma_f32 v[130:131], v[56:57], v[168:169], v[130:131] op_sel:[0,1,0]
	v_pk_add_f32 v[10:11], v[10:11], v[132:133]
	v_pk_add_f32 v[8:9], v[8:9], v[130:131]
	v_pk_mul_f32 v[136:137], v[50:51], v[170:171] op_sel:[0,1]
	v_pk_mul_f32 v[134:135], v[48:49], v[170:171] op_sel:[0,1]
	v_pk_fma_f32 v[136:137], v[46:47], v[170:171], v[136:137] op_sel_hi:[1,0,1]
	v_pk_fma_f32 v[134:135], v[44:45], v[170:171], v[134:135] op_sel_hi:[1,0,1]
	v_pk_fma_f32 v[136:137], v[54:55], v[172:173], v[136:137] op_sel_hi:[1,0,1]
	v_pk_fma_f32 v[134:135], v[52:53], v[172:173], v[134:135] op_sel_hi:[1,0,1]
	v_pk_fma_f32 v[136:137], v[58:59], v[172:173], v[136:137] op_sel:[0,1,0]
	v_pk_fma_f32 v[134:135], v[56:57], v[172:173], v[134:135] op_sel:[0,1,0]
	v_pk_add_f32 v[6:7], v[6:7], v[136:137]
	v_pk_add_f32 v[4:5], v[4:5], v[134:135]
	v_pk_mul_f32 v[140:141], v[50:51], v[174:175] op_sel:[0,1]
	v_pk_mul_f32 v[138:139], v[48:49], v[174:175] op_sel:[0,1]
	v_pk_fma_f32 v[140:141], v[46:47], v[174:175], v[140:141] op_sel_hi:[1,0,1]
	v_pk_fma_f32 v[138:139], v[44:45], v[174:175], v[138:139] op_sel_hi:[1,0,1]
	v_pk_fma_f32 v[140:141], v[54:55], v[176:177], v[140:141] op_sel_hi:[1,0,1]
	v_pk_fma_f32 v[138:139], v[52:53], v[176:177], v[138:139] op_sel_hi:[1,0,1]
	v_pk_fma_f32 v[140:141], v[58:59], v[176:177], v[140:141] op_sel:[0,1,0]
	v_pk_fma_f32 v[138:139], v[56:57], v[176:177], v[138:139] op_sel:[0,1,0]
	v_pk_add_f32 v[2:3], v[2:3], v[140:141]
	v_pk_add_f32 v[0:1], v[0:1], v[138:139]
	v_mov_b32_e32 v43, s10
	ds_read_b128 v[146:149], v43
	ds_read_b128 v[150:153], v43 offset:4096
	ds_read_b128 v[154:157], v43 offset:8192
	ds_read_b128 v[158:161], v43 offset:12288
	ds_read_b128 v[162:165], v43 offset:16384
	ds_read_b128 v[166:169], v43 offset:20480
	ds_read_b128 v[170:173], v43 offset:24576
	ds_read_b128 v[174:177], v43 offset:28672
	s_add_i32 s10, s10, 16
	v_lshl_add_u64 v[38:39], v[36:37], 0, s[6:7]
	global_load_dwordx4 v[44:47], v[38:39], off nt
	v_lshl_add_u64 v[38:39], v[178:179], 0, s[6:7]
	global_load_dwordx4 v[48:51], v[38:39], off nt
	v_lshl_add_u64 v[38:39], v[180:181], 0, s[6:7]
	global_load_dwordx4 v[52:55], v[38:39], off nt
	v_lshl_add_u64 v[38:39], v[182:183], 0, s[6:7]
	global_load_dwordx4 v[56:59], v[38:39], off nt
	s_add_u32 s6, s6, 0x24000
	s_min_u32 s6, s6, 0x45c000
	s_waitcnt vmcnt(12)
	s_waitcnt lgkmcnt(0)
	v_pk_mul_f32 v[128:129], v[66:67], v[146:147] op_sel:[0,1]
	v_pk_mul_f32 v[126:127], v[64:65], v[146:147] op_sel:[0,1]
	v_pk_fma_f32 v[128:129], v[62:63], v[146:147], v[128:129] op_sel_hi:[1,0,1]
	v_pk_fma_f32 v[126:127], v[60:61], v[146:147], v[126:127] op_sel_hi:[1,0,1]
	v_pk_fma_f32 v[128:129], v[70:71], v[148:149], v[128:129] op_sel_hi:[1,0,1]
	v_pk_fma_f32 v[126:127], v[68:69], v[148:149], v[126:127] op_sel_hi:[1,0,1]
	v_pk_fma_f32 v[128:129], v[74:75], v[148:149], v[128:129] op_sel:[0,1,0]
	v_pk_fma_f32 v[126:127], v[72:73], v[148:149], v[126:127] op_sel:[0,1,0]
	v_pk_add_f32 v[30:31], v[30:31], v[128:129]
	v_pk_add_f32 v[28:29], v[28:29], v[126:127]
	v_pk_mul_f32 v[132:133], v[66:67], v[150:151] op_sel:[0,1]
	v_pk_mul_f32 v[130:131], v[64:65], v[150:151] op_sel:[0,1]
	v_pk_fma_f32 v[132:133], v[62:63], v[150:151], v[132:133] op_sel_hi:[1,0,1]
	v_pk_fma_f32 v[130:131], v[60:61], v[150:151], v[130:131] op_sel_hi:[1,0,1]
	v_pk_fma_f32 v[132:133], v[70:71], v[152:153], v[132:133] op_sel_hi:[1,0,1]
	v_pk_fma_f32 v[130:131], v[68:69], v[152:153], v[130:131] op_sel_hi:[1,0,1]
	v_pk_fma_f32 v[132:133], v[74:75], v[152:153], v[132:133] op_sel:[0,1,0]
	v_pk_fma_f32 v[130:131], v[72:73], v[152:153], v[130:131] op_sel:[0,1,0]
	v_pk_add_f32 v[26:27], v[26:27], v[132:133]
	v_pk_add_f32 v[24:25], v[24:25], v[130:131]
	v_pk_mul_f32 v[136:137], v[66:67], v[154:155] op_sel:[0,1]
	v_pk_mul_f32 v[134:135], v[64:65], v[154:155] op_sel:[0,1]
	v_pk_fma_f32 v[136:137], v[62:63], v[154:155], v[136:137] op_sel_hi:[1,0,1]
	v_pk_fma_f32 v[134:135], v[60:61], v[154:155], v[134:135] op_sel_hi:[1,0,1]
	v_pk_fma_f32 v[136:137], v[70:71], v[156:157], v[136:137] op_sel_hi:[1,0,1]
	v_pk_fma_f32 v[134:135], v[68:69], v[156:157], v[134:135] op_sel_hi:[1,0,1]
	v_pk_fma_f32 v[136:137], v[74:75], v[156:157], v[136:137] op_sel:[0,1,0]
	v_pk_fma_f32 v[134:135], v[72:73], v[156:157], v[134:135] op_sel:[0,1,0]
	v_pk_add_f32 v[22:23], v[22:23], v[136:137]
	v_pk_add_f32 v[20:21], v[20:21], v[134:135]
	v_pk_mul_f32 v[140:141], v[66:67], v[158:159] op_sel:[0,1]
	v_pk_mul_f32 v[138:139], v[64:65], v[158:159] op_sel:[0,1]
	v_pk_fma_f32 v[140:141], v[62:63], v[158:159], v[140:141] op_sel_hi:[1,0,1]
	v_pk_fma_f32 v[138:139], v[60:61], v[158:159], v[138:139] op_sel_hi:[1,0,1]
	v_pk_fma_f32 v[140:141], v[70:71], v[160:161], v[140:141] op_sel_hi:[1,0,1]
	v_pk_fma_f32 v[138:139], v[68:69], v[160:161], v[138:139] op_sel_hi:[1,0,1]
	v_pk_fma_f32 v[140:141], v[74:75], v[160:161], v[140:141] op_sel:[0,1,0]
	v_pk_fma_f32 v[138:139], v[72:73], v[160:161], v[138:139] op_sel:[0,1,0]
	v_pk_add_f32 v[18:19], v[18:19], v[140:141]
	v_pk_add_f32 v[16:17], v[16:17], v[138:139]
	v_pk_mul_f32 v[128:129], v[66:67], v[162:163] op_sel:[0,1]
	v_pk_mul_f32 v[126:127], v[64:65], v[162:163] op_sel:[0,1]
	v_pk_fma_f32 v[128:129], v[62:63], v[162:163], v[128:129] op_sel_hi:[1,0,1]
	v_pk_fma_f32 v[126:127], v[60:61], v[162:163], v[126:127] op_sel_hi:[1,0,1]
	v_pk_fma_f32 v[128:129], v[70:71], v[164:165], v[128:129] op_sel_hi:[1,0,1]
	v_pk_fma_f32 v[126:127], v[68:69], v[164:165], v[126:127] op_sel_hi:[1,0,1]
	v_pk_fma_f32 v[128:129], v[74:75], v[164:165], v[128:129] op_sel:[0,1,0]
	v_pk_fma_f32 v[126:127], v[72:73], v[164:165], v[126:127] op_sel:[0,1,0]
	v_pk_add_f32 v[14:15], v[14:15], v[128:129]
	v_pk_add_f32 v[12:13], v[12:13], v[126:127]
	v_pk_mul_f32 v[132:133], v[66:67], v[166:167] op_sel:[0,1]
	v_pk_mul_f32 v[130:131], v[64:65], v[166:167] op_sel:[0,1]
	v_pk_fma_f32 v[132:133], v[62:63], v[166:167], v[132:133] op_sel_hi:[1,0,1]
	v_pk_fma_f32 v[130:131], v[60:61], v[166:167], v[130:131] op_sel_hi:[1,0,1]
	v_pk_fma_f32 v[132:133], v[70:71], v[168:169], v[132:133] op_sel_hi:[1,0,1]
	v_pk_fma_f32 v[130:131], v[68:69], v[168:169], v[130:131] op_sel_hi:[1,0,1]
	v_pk_fma_f32 v[132:133], v[74:75], v[168:169], v[132:133] op_sel:[0,1,0]
	v_pk_fma_f32 v[130:131], v[72:73], v[168:169], v[130:131] op_sel:[0,1,0]
	v_pk_add_f32 v[10:11], v[10:11], v[132:133]
	v_pk_add_f32 v[8:9], v[8:9], v[130:131]
	v_pk_mul_f32 v[136:137], v[66:67], v[170:171] op_sel:[0,1]
	v_pk_mul_f32 v[134:135], v[64:65], v[170:171] op_sel:[0,1]
	v_pk_fma_f32 v[136:137], v[62:63], v[170:171], v[136:137] op_sel_hi:[1,0,1]
	v_pk_fma_f32 v[134:135], v[60:61], v[170:171], v[134:135] op_sel_hi:[1,0,1]
	v_pk_fma_f32 v[136:137], v[70:71], v[172:173], v[136:137] op_sel_hi:[1,0,1]
	v_pk_fma_f32 v[134:135], v[68:69], v[172:173], v[134:135] op_sel_hi:[1,0,1]
	v_pk_fma_f32 v[136:137], v[74:75], v[172:173], v[136:137] op_sel:[0,1,0]
	v_pk_fma_f32 v[134:135], v[72:73], v[172:173], v[134:135] op_sel:[0,1,0]
	v_pk_add_f32 v[6:7], v[6:7], v[136:137]
	v_pk_add_f32 v[4:5], v[4:5], v[134:135]
	v_pk_mul_f32 v[140:141], v[66:67], v[174:175] op_sel:[0,1]
	v_pk_mul_f32 v[138:139], v[64:65], v[174:175] op_sel:[0,1]
	v_pk_fma_f32 v[140:141], v[62:63], v[174:175], v[140:141] op_sel_hi:[1,0,1]
	v_pk_fma_f32 v[138:139], v[60:61], v[174:175], v[138:139] op_sel_hi:[1,0,1]
	v_pk_fma_f32 v[140:141], v[70:71], v[176:177], v[140:141] op_sel_hi:[1,0,1]
	v_pk_fma_f32 v[138:139], v[68:69], v[176:177], v[138:139] op_sel_hi:[1,0,1]
	v_pk_fma_f32 v[140:141], v[74:75], v[176:177], v[140:141] op_sel:[0,1,0]
	v_pk_fma_f32 v[138:139], v[72:73], v[176:177], v[138:139] op_sel:[0,1,0]
	v_pk_add_f32 v[2:3], v[2:3], v[140:141]
	v_pk_add_f32 v[0:1], v[0:1], v[138:139]
	v_mov_b32_e32 v43, s10
	ds_read_b128 v[146:149], v43
	ds_read_b128 v[150:153], v43 offset:4096
	ds_read_b128 v[154:157], v43 offset:8192
	ds_read_b128 v[158:161], v43 offset:12288
	ds_read_b128 v[162:165], v43 offset:16384
	ds_read_b128 v[166:169], v43 offset:20480
	ds_read_b128 v[170:173], v43 offset:24576
	ds_read_b128 v[174:177], v43 offset:28672
	s_add_i32 s10, s10, 16
	v_lshl_add_u64 v[38:39], v[36:37], 0, s[6:7]
	global_load_dwordx4 v[60:63], v[38:39], off nt
	v_lshl_add_u64 v[38:39], v[178:179], 0, s[6:7]
	global_load_dwordx4 v[64:67], v[38:39], off nt
	v_lshl_add_u64 v[38:39], v[180:181], 0, s[6:7]
	global_load_dwordx4 v[68:71], v[38:39], off nt
	v_lshl_add_u64 v[38:39], v[182:183], 0, s[6:7]
	global_load_dwordx4 v[72:75], v[38:39], off nt
	s_add_u32 s6, s6, 0x24000
	s_min_u32 s6, s6, 0x45c000
	s_waitcnt vmcnt(12)
	s_waitcnt lgkmcnt(0)
	v_pk_mul_f32 v[128:129], v[100:101], v[146:147] op_sel:[0,1]
	v_pk_mul_f32 v[126:127], v[98:99], v[146:147] op_sel:[0,1]
	v_pk_fma_f32 v[128:129], v[96:97], v[146:147], v[128:129] op_sel_hi:[1,0,1]
	v_pk_fma_f32 v[126:127], v[94:95], v[146:147], v[126:127] op_sel_hi:[1,0,1]
	v_pk_fma_f32 v[128:129], v[104:105], v[148:149], v[128:129] op_sel_hi:[1,0,1]
	v_pk_fma_f32 v[126:127], v[102:103], v[148:149], v[126:127] op_sel_hi:[1,0,1]
	v_pk_fma_f32 v[128:129], v[108:109], v[148:149], v[128:129] op_sel:[0,1,0]
	v_pk_fma_f32 v[126:127], v[106:107], v[148:149], v[126:127] op_sel:[0,1,0]
	v_pk_add_f32 v[30:31], v[30:31], v[128:129]
	v_pk_add_f32 v[28:29], v[28:29], v[126:127]
	v_pk_mul_f32 v[132:133], v[100:101], v[150:151] op_sel:[0,1]
	v_pk_mul_f32 v[130:131], v[98:99], v[150:151] op_sel:[0,1]
	v_pk_fma_f32 v[132:133], v[96:97], v[150:151], v[132:133] op_sel_hi:[1,0,1]
	v_pk_fma_f32 v[130:131], v[94:95], v[150:151], v[130:131] op_sel_hi:[1,0,1]
	v_pk_fma_f32 v[132:133], v[104:105], v[152:153], v[132:133] op_sel_hi:[1,0,1]
	v_pk_fma_f32 v[130:131], v[102:103], v[152:153], v[130:131] op_sel_hi:[1,0,1]
	v_pk_fma_f32 v[132:133], v[108:109], v[152:153], v[132:133] op_sel:[0,1,0]
	v_pk_fma_f32 v[130:131], v[106:107], v[152:153], v[130:131] op_sel:[0,1,0]
	v_pk_add_f32 v[26:27], v[26:27], v[132:133]
	v_pk_add_f32 v[24:25], v[24:25], v[130:131]
	v_pk_mul_f32 v[136:137], v[100:101], v[154:155] op_sel:[0,1]
	v_pk_mul_f32 v[134:135], v[98:99], v[154:155] op_sel:[0,1]
	v_pk_fma_f32 v[136:137], v[96:97], v[154:155], v[136:137] op_sel_hi:[1,0,1]
	v_pk_fma_f32 v[134:135], v[94:95], v[154:155], v[134:135] op_sel_hi:[1,0,1]
	v_pk_fma_f32 v[136:137], v[104:105], v[156:157], v[136:137] op_sel_hi:[1,0,1]
	v_pk_fma_f32 v[134:135], v[102:103], v[156:157], v[134:135] op_sel_hi:[1,0,1]
	v_pk_fma_f32 v[136:137], v[108:109], v[156:157], v[136:137] op_sel:[0,1,0]
	v_pk_fma_f32 v[134:135], v[106:107], v[156:157], v[134:135] op_sel:[0,1,0]
	v_pk_add_f32 v[22:23], v[22:23], v[136:137]
	v_pk_add_f32 v[20:21], v[20:21], v[134:135]
	v_pk_mul_f32 v[140:141], v[100:101], v[158:159] op_sel:[0,1]
	v_pk_mul_f32 v[138:139], v[98:99], v[158:159] op_sel:[0,1]
	v_pk_fma_f32 v[140:141], v[96:97], v[158:159], v[140:141] op_sel_hi:[1,0,1]
	v_pk_fma_f32 v[138:139], v[94:95], v[158:159], v[138:139] op_sel_hi:[1,0,1]
	v_pk_fma_f32 v[140:141], v[104:105], v[160:161], v[140:141] op_sel_hi:[1,0,1]
	v_pk_fma_f32 v[138:139], v[102:103], v[160:161], v[138:139] op_sel_hi:[1,0,1]
	v_pk_fma_f32 v[140:141], v[108:109], v[160:161], v[140:141] op_sel:[0,1,0]
	v_pk_fma_f32 v[138:139], v[106:107], v[160:161], v[138:139] op_sel:[0,1,0]
	v_pk_add_f32 v[18:19], v[18:19], v[140:141]
	v_pk_add_f32 v[16:17], v[16:17], v[138:139]
	v_pk_mul_f32 v[128:129], v[100:101], v[162:163] op_sel:[0,1]
	v_pk_mul_f32 v[126:127], v[98:99], v[162:163] op_sel:[0,1]
	v_pk_fma_f32 v[128:129], v[96:97], v[162:163], v[128:129] op_sel_hi:[1,0,1]
	v_pk_fma_f32 v[126:127], v[94:95], v[162:163], v[126:127] op_sel_hi:[1,0,1]
	v_pk_fma_f32 v[128:129], v[104:105], v[164:165], v[128:129] op_sel_hi:[1,0,1]
	v_pk_fma_f32 v[126:127], v[102:103], v[164:165], v[126:127] op_sel_hi:[1,0,1]
	v_pk_fma_f32 v[128:129], v[108:109], v[164:165], v[128:129] op_sel:[0,1,0]
	v_pk_fma_f32 v[126:127], v[106:107], v[164:165], v[126:127] op_sel:[0,1,0]
	v_pk_add_f32 v[14:15], v[14:15], v[128:129]
	v_pk_add_f32 v[12:13], v[12:13], v[126:127]
	v_pk_mul_f32 v[132:133], v[100:101], v[166:167] op_sel:[0,1]
	v_pk_mul_f32 v[130:131], v[98:99], v[166:167] op_sel:[0,1]
	v_pk_fma_f32 v[132:133], v[96:97], v[166:167], v[132:133] op_sel_hi:[1,0,1]
	v_pk_fma_f32 v[130:131], v[94:95], v[166:167], v[130:131] op_sel_hi:[1,0,1]
	v_pk_fma_f32 v[132:133], v[104:105], v[168:169], v[132:133] op_sel_hi:[1,0,1]
	v_pk_fma_f32 v[130:131], v[102:103], v[168:169], v[130:131] op_sel_hi:[1,0,1]
	v_pk_fma_f32 v[132:133], v[108:109], v[168:169], v[132:133] op_sel:[0,1,0]
	v_pk_fma_f32 v[130:131], v[106:107], v[168:169], v[130:131] op_sel:[0,1,0]
	v_pk_add_f32 v[10:11], v[10:11], v[132:133]
	v_pk_add_f32 v[8:9], v[8:9], v[130:131]
	v_pk_mul_f32 v[136:137], v[100:101], v[170:171] op_sel:[0,1]
	v_pk_mul_f32 v[134:135], v[98:99], v[170:171] op_sel:[0,1]
	v_pk_fma_f32 v[136:137], v[96:97], v[170:171], v[136:137] op_sel_hi:[1,0,1]
	v_pk_fma_f32 v[134:135], v[94:95], v[170:171], v[134:135] op_sel_hi:[1,0,1]
	v_pk_fma_f32 v[136:137], v[104:105], v[172:173], v[136:137] op_sel_hi:[1,0,1]
	v_pk_fma_f32 v[134:135], v[102:103], v[172:173], v[134:135] op_sel_hi:[1,0,1]
	v_pk_fma_f32 v[136:137], v[108:109], v[172:173], v[136:137] op_sel:[0,1,0]
	v_pk_fma_f32 v[134:135], v[106:107], v[172:173], v[134:135] op_sel:[0,1,0]
	v_pk_add_f32 v[6:7], v[6:7], v[136:137]
	v_pk_add_f32 v[4:5], v[4:5], v[134:135]
	v_pk_mul_f32 v[140:141], v[100:101], v[174:175] op_sel:[0,1]
	v_pk_mul_f32 v[138:139], v[98:99], v[174:175] op_sel:[0,1]
	v_pk_fma_f32 v[140:141], v[96:97], v[174:175], v[140:141] op_sel_hi:[1,0,1]
	v_pk_fma_f32 v[138:139], v[94:95], v[174:175], v[138:139] op_sel_hi:[1,0,1]
	v_pk_fma_f32 v[140:141], v[104:105], v[176:177], v[140:141] op_sel_hi:[1,0,1]
	v_pk_fma_f32 v[138:139], v[102:103], v[176:177], v[138:139] op_sel_hi:[1,0,1]
	v_pk_fma_f32 v[140:141], v[108:109], v[176:177], v[140:141] op_sel:[0,1,0]
	v_pk_fma_f32 v[138:139], v[106:107], v[176:177], v[138:139] op_sel:[0,1,0]
	v_pk_add_f32 v[2:3], v[2:3], v[140:141]
	v_pk_add_f32 v[0:1], v[0:1], v[138:139]
	v_mov_b32_e32 v43, s10
	ds_read_b128 v[146:149], v43
	ds_read_b128 v[150:153], v43 offset:4096
	ds_read_b128 v[154:157], v43 offset:8192
	ds_read_b128 v[158:161], v43 offset:12288
	ds_read_b128 v[162:165], v43 offset:16384
	ds_read_b128 v[166:169], v43 offset:20480
	ds_read_b128 v[170:173], v43 offset:24576
	ds_read_b128 v[174:177], v43 offset:28672
	s_add_i32 s10, s10, 16
	v_lshl_add_u64 v[38:39], v[36:37], 0, s[6:7]
	global_load_dwordx4 v[94:97], v[38:39], off nt
	v_lshl_add_u64 v[38:39], v[178:179], 0, s[6:7]
	global_load_dwordx4 v[98:101], v[38:39], off nt
	v_lshl_add_u64 v[38:39], v[180:181], 0, s[6:7]
	global_load_dwordx4 v[102:105], v[38:39], off nt
	v_lshl_add_u64 v[38:39], v[182:183], 0, s[6:7]
	global_load_dwordx4 v[106:109], v[38:39], off nt
	s_add_u32 s6, s6, 0x24000
	s_min_u32 s6, s6, 0x45c000
	s_waitcnt vmcnt(12)
	s_waitcnt lgkmcnt(0)
	v_pk_mul_f32 v[128:129], v[116:117], v[146:147] op_sel:[0,1]
	v_pk_mul_f32 v[126:127], v[114:115], v[146:147] op_sel:[0,1]
	v_pk_fma_f32 v[128:129], v[112:113], v[146:147], v[128:129] op_sel_hi:[1,0,1]
	v_pk_fma_f32 v[126:127], v[110:111], v[146:147], v[126:127] op_sel_hi:[1,0,1]
	v_pk_fma_f32 v[128:129], v[120:121], v[148:149], v[128:129] op_sel_hi:[1,0,1]
	v_pk_fma_f32 v[126:127], v[118:119], v[148:149], v[126:127] op_sel_hi:[1,0,1]
	v_pk_fma_f32 v[128:129], v[124:125], v[148:149], v[128:129] op_sel:[0,1,0]
	v_pk_fma_f32 v[126:127], v[122:123], v[148:149], v[126:127] op_sel:[0,1,0]
	v_pk_add_f32 v[30:31], v[30:31], v[128:129]
	v_pk_add_f32 v[28:29], v[28:29], v[126:127]
	v_pk_mul_f32 v[132:133], v[116:117], v[150:151] op_sel:[0,1]
	v_pk_mul_f32 v[130:131], v[114:115], v[150:151] op_sel:[0,1]
	v_pk_fma_f32 v[132:133], v[112:113], v[150:151], v[132:133] op_sel_hi:[1,0,1]
	v_pk_fma_f32 v[130:131], v[110:111], v[150:151], v[130:131] op_sel_hi:[1,0,1]
	v_pk_fma_f32 v[132:133], v[120:121], v[152:153], v[132:133] op_sel_hi:[1,0,1]
	v_pk_fma_f32 v[130:131], v[118:119], v[152:153], v[130:131] op_sel_hi:[1,0,1]
	v_pk_fma_f32 v[132:133], v[124:125], v[152:153], v[132:133] op_sel:[0,1,0]
	v_pk_fma_f32 v[130:131], v[122:123], v[152:153], v[130:131] op_sel:[0,1,0]
	v_pk_add_f32 v[26:27], v[26:27], v[132:133]
	v_pk_add_f32 v[24:25], v[24:25], v[130:131]
	v_pk_mul_f32 v[136:137], v[116:117], v[154:155] op_sel:[0,1]
	v_pk_mul_f32 v[134:135], v[114:115], v[154:155] op_sel:[0,1]
	v_pk_fma_f32 v[136:137], v[112:113], v[154:155], v[136:137] op_sel_hi:[1,0,1]
	v_pk_fma_f32 v[134:135], v[110:111], v[154:155], v[134:135] op_sel_hi:[1,0,1]
	v_pk_fma_f32 v[136:137], v[120:121], v[156:157], v[136:137] op_sel_hi:[1,0,1]
	v_pk_fma_f32 v[134:135], v[118:119], v[156:157], v[134:135] op_sel_hi:[1,0,1]
	v_pk_fma_f32 v[136:137], v[124:125], v[156:157], v[136:137] op_sel:[0,1,0]
	v_pk_fma_f32 v[134:135], v[122:123], v[156:157], v[134:135] op_sel:[0,1,0]
	v_pk_add_f32 v[22:23], v[22:23], v[136:137]
	v_pk_add_f32 v[20:21], v[20:21], v[134:135]
	v_pk_mul_f32 v[140:141], v[116:117], v[158:159] op_sel:[0,1]
	v_pk_mul_f32 v[138:139], v[114:115], v[158:159] op_sel:[0,1]
	v_pk_fma_f32 v[140:141], v[112:113], v[158:159], v[140:141] op_sel_hi:[1,0,1]
	v_pk_fma_f32 v[138:139], v[110:111], v[158:159], v[138:139] op_sel_hi:[1,0,1]
	v_pk_fma_f32 v[140:141], v[120:121], v[160:161], v[140:141] op_sel_hi:[1,0,1]
	v_pk_fma_f32 v[138:139], v[118:119], v[160:161], v[138:139] op_sel_hi:[1,0,1]
	v_pk_fma_f32 v[140:141], v[124:125], v[160:161], v[140:141] op_sel:[0,1,0]
	v_pk_fma_f32 v[138:139], v[122:123], v[160:161], v[138:139] op_sel:[0,1,0]
	v_pk_add_f32 v[18:19], v[18:19], v[140:141]
	v_pk_add_f32 v[16:17], v[16:17], v[138:139]
	v_pk_mul_f32 v[128:129], v[116:117], v[162:163] op_sel:[0,1]
	v_pk_mul_f32 v[126:127], v[114:115], v[162:163] op_sel:[0,1]
	v_pk_fma_f32 v[128:129], v[112:113], v[162:163], v[128:129] op_sel_hi:[1,0,1]
	v_pk_fma_f32 v[126:127], v[110:111], v[162:163], v[126:127] op_sel_hi:[1,0,1]
	v_pk_fma_f32 v[128:129], v[120:121], v[164:165], v[128:129] op_sel_hi:[1,0,1]
	v_pk_fma_f32 v[126:127], v[118:119], v[164:165], v[126:127] op_sel_hi:[1,0,1]
	v_pk_fma_f32 v[128:129], v[124:125], v[164:165], v[128:129] op_sel:[0,1,0]
	v_pk_fma_f32 v[126:127], v[122:123], v[164:165], v[126:127] op_sel:[0,1,0]
	v_pk_add_f32 v[14:15], v[14:15], v[128:129]
	v_pk_add_f32 v[12:13], v[12:13], v[126:127]
	v_pk_mul_f32 v[132:133], v[116:117], v[166:167] op_sel:[0,1]
	v_pk_mul_f32 v[130:131], v[114:115], v[166:167] op_sel:[0,1]
	v_pk_fma_f32 v[132:133], v[112:113], v[166:167], v[132:133] op_sel_hi:[1,0,1]
	v_pk_fma_f32 v[130:131], v[110:111], v[166:167], v[130:131] op_sel_hi:[1,0,1]
	v_pk_fma_f32 v[132:133], v[120:121], v[168:169], v[132:133] op_sel_hi:[1,0,1]
	v_pk_fma_f32 v[130:131], v[118:119], v[168:169], v[130:131] op_sel_hi:[1,0,1]
	v_pk_fma_f32 v[132:133], v[124:125], v[168:169], v[132:133] op_sel:[0,1,0]
	v_pk_fma_f32 v[130:131], v[122:123], v[168:169], v[130:131] op_sel:[0,1,0]
	v_pk_add_f32 v[10:11], v[10:11], v[132:133]
	v_pk_add_f32 v[8:9], v[8:9], v[130:131]
	v_pk_mul_f32 v[136:137], v[116:117], v[170:171] op_sel:[0,1]
	v_pk_mul_f32 v[134:135], v[114:115], v[170:171] op_sel:[0,1]
	v_pk_fma_f32 v[136:137], v[112:113], v[170:171], v[136:137] op_sel_hi:[1,0,1]
	v_pk_fma_f32 v[134:135], v[110:111], v[170:171], v[134:135] op_sel_hi:[1,0,1]
	v_pk_fma_f32 v[136:137], v[120:121], v[172:173], v[136:137] op_sel_hi:[1,0,1]
	v_pk_fma_f32 v[134:135], v[118:119], v[172:173], v[134:135] op_sel_hi:[1,0,1]
	v_pk_fma_f32 v[136:137], v[124:125], v[172:173], v[136:137] op_sel:[0,1,0]
	v_pk_fma_f32 v[134:135], v[122:123], v[172:173], v[134:135] op_sel:[0,1,0]
	v_pk_add_f32 v[6:7], v[6:7], v[136:137]
	v_pk_add_f32 v[4:5], v[4:5], v[134:135]
	v_pk_mul_f32 v[140:141], v[116:117], v[174:175] op_sel:[0,1]
	v_pk_mul_f32 v[138:139], v[114:115], v[174:175] op_sel:[0,1]
	v_pk_fma_f32 v[140:141], v[112:113], v[174:175], v[140:141] op_sel_hi:[1,0,1]
	v_pk_fma_f32 v[138:139], v[110:111], v[174:175], v[138:139] op_sel_hi:[1,0,1]
	v_pk_fma_f32 v[140:141], v[120:121], v[176:177], v[140:141] op_sel_hi:[1,0,1]
	v_pk_fma_f32 v[138:139], v[118:119], v[176:177], v[138:139] op_sel_hi:[1,0,1]
	v_pk_fma_f32 v[140:141], v[124:125], v[176:177], v[140:141] op_sel:[0,1,0]
	v_pk_fma_f32 v[138:139], v[122:123], v[176:177], v[138:139] op_sel:[0,1,0]
	v_pk_add_f32 v[2:3], v[2:3], v[140:141]
	v_pk_add_f32 v[0:1], v[0:1], v[138:139]
	s_cmp_lg_u32 s10, s11
	s_cbranch_scc1 .Lada_k
	s_waitcnt vmcnt(0)
	ds_write_b128 v40, v[28:31] offset:32768
	ds_write_b128 v40, v[24:27] offset:33792
	ds_write_b128 v40, v[20:23] offset:34816
	ds_write_b128 v40, v[16:19] offset:35840
	ds_write_b128 v40, v[12:15] offset:36864
	ds_write_b128 v40, v[8:11] offset:37888
	ds_write_b128 v40, v[4:7] offset:38912
	ds_write_b128 v40, v[0:3] offset:39936
	v_mov_b32_e32 v0, s15
	s_waitcnt lgkmcnt(0)
	s_barrier
	ds_read_b64 v[0:1], v0
	s_mul_i32 s11, s0, 0x9000
	s_mul_hi_i32 s10, s0, 0x9000
	v_lshl_add_u64 v[44:45], s[0:1], 3, v[32:33]
	v_mov_b64_e32 v[46:47], s[12:13]
	s_waitcnt lgkmcnt(0)
	v_readfirstlane_b32 s7, v0
	v_readfirstlane_b32 s6, v1
	s_add_u32 s7, s7, s11
	s_addc_u32 s10, s6, s10
	s_add_u32 s6, s7, s4
	s_addc_u32 s7, s10, s5
	v_mad_u64_u32 v[46:47], s[0:1], v44, s54, v[46:47]
	global_load_dwordx4 v[0:3], v144, s[6:7]
	ds_read_b128 v[4:7], v41 offset:32768
	ds_read_b128 v[8:11], v41 offset:40960
	ds_read_b128 v[12:15], v41 offset:49152
	ds_read_b128 v[16:19], v41 offset:57344
	ds_read_b128 v[20:23], v42 offset:32768
	ds_read_b128 v[24:27], v42 offset:40960
	ds_read_b128 v[28:31], v42 offset:49152
	ds_read_b128 v[36:39], v42 offset:57344
	v_mad_i32_i24 v47, v45, s54, v47
	v_lshl_add_u64 v[44:45], v[46:47], 0, s[4:5]
	s_add_i32 s9, s9, s33
	v_lshl_add_u64 v[44:45], v[44:45], 0, v[144:145]
	s_cmpk_gt_i32 s9, 0x8f
	s_waitcnt vmcnt(0) lgkmcnt(7)
	v_pk_add_f32 v[2:3], v[2:3], v[6:7]
	v_pk_add_f32 v[0:1], v[0:1], v[4:5]
	s_waitcnt lgkmcnt(6)
	v_pk_add_f32 v[2:3], v[2:3], v[10:11]
	v_pk_add_f32 v[0:1], v[0:1], v[8:9]
	s_waitcnt lgkmcnt(5)
	v_pk_add_f32 v[2:3], v[2:3], v[14:15]
	v_pk_add_f32 v[0:1], v[0:1], v[12:13]
	s_waitcnt lgkmcnt(4)
	v_pk_add_f32 v[2:3], v[2:3], v[18:19]
	v_pk_add_f32 v[0:1], v[0:1], v[16:17]
	s_waitcnt lgkmcnt(3)
	v_pk_add_f32 v[2:3], v[2:3], v[22:23]
	v_pk_add_f32 v[0:1], v[0:1], v[20:21]
	s_waitcnt lgkmcnt(2)
	v_pk_add_f32 v[2:3], v[2:3], v[26:27]
	v_pk_add_f32 v[0:1], v[0:1], v[24:25]
	s_waitcnt lgkmcnt(1)
	v_pk_add_f32 v[2:3], v[2:3], v[30:31]
	v_pk_add_f32 v[0:1], v[0:1], v[28:29]
	s_waitcnt lgkmcnt(0)
	v_pk_add_f32 v[2:3], v[2:3], v[38:39]
	v_pk_add_f32 v[0:1], v[0:1], v[36:37]
	global_store_dwordx4 v[44:45], v[0:3], off
	s_barrier
	s_cbranch_scc0 .LBB0_686
